# scan start: decay and first-chunk u loads issued before the first record DMA (one memory round trip instead of two)
# speedup vs baseline: 1.0053x; 1.0053x over previous
.LBB0_374:
	s_lshl_b32 s78, s26, 5
	s_mul_i32 s4, s26, 0x1e8000
	s_mul_hi_i32 s13, s78, 0xf400
	s_add_u32 s12, s3, s4
	s_addc_u32 s13, s19, s13
	v_readfirstlane_b32 s4, v212
	v_and_b32_e32 v26, 63, v212
	s_lshr_b32 s4, s4, 6
	s_lshl_b32 s27, s4, 10
	v_lshl_add_u32 v26, v26, 4, s27
	s_mov_b32 s28, s4
	s_ashr_i32 s79, s78, 31
	s_and_b64 vcc, exec, s[6:7]
	s_cbranch_vccz .Lscan_pre_skip
	v_or_b32_e32 v0, s78, v210
	v_ashrrev_i32_e32 v1, 31, v0
	s_lshl_b64 s[30:31], s[78:79], 14
	v_lshl_add_u64 v[0:1], v[0:1], 2, s[8:9]
	v_lshl_add_u64 v[24:25], v[214:215], 0, s[30:31]
	global_load_dword v164, v[0:1], off
	global_load_dwordx4 v[0:3], v[24:25], off
	global_load_dwordx4 v[4:7], v[24:25], off offset:1024
	global_load_dwordx4 v[8:11], v[24:25], off offset:2048
	global_load_dwordx4 v[12:15], v[24:25], off offset:3072
.Lscan_pre_skip:
.Lscan_r0_loop:
	s_lshl_b32 s29, s28, 10
	s_mov_b32 m0, s29
	s_nop 0
	global_load_lds_dwordx4 v26, s[12:13]
	v_add_u32_e32 v26, 0x2000, v26
	s_add_i32 s28, s28, 8
	s_cmp_lt_u32 s28, 61
	s_cbranch_scc1 .Lscan_r0_loop
	s_waitcnt vmcnt(0)
.LBB0_377:
	s_or_b64 exec, exec, s[76:77]
	s_waitcnt lgkmcnt(0)
	s_barrier
	s_ashr_i32 s79, s78, 31
	s_mov_b64 s[76:77], -1
	s_and_b64 vcc, exec, s[6:7]
	s_cbranch_vccz .LBB0_381
	s_waitcnt vmcnt(16)
	v_mov_b32_e32 v242, 0x3020706
	v_mov_b32_e32 v243, 0x5040100
	v_cndmask_b32_e64 v242, v242, v243, s[40:41]
	s_ashr_i32 s76, s26, 2
	s_lshl_b32 s4, s24, 1
	s_ashr_i32 s77, s76, 31
	s_and_b32 s4, s4, 0x300
	s_lshl_b64 s[76:77], s[76:77], 21
	s_or_b32 s4, s76, s4
	s_add_u32 s27, s17, s4
	v_mov_b32_e32 v32, 0
	s_addc_u32 s28, s20, s77
	s_mov_b32 s29, 0
	s_mov_b64 s[78:79], 0
	v_mov_b32_e32 v33, v32
	v_mov_b32_e32 v34, v32
	v_mov_b32_e32 v35, v32
	v_mov_b32_e32 v36, v32
	v_mov_b32_e32 v37, v32
	v_mov_b32_e32 v38, v32
	v_mov_b32_e32 v39, v32
	v_mov_b32_e32 v40, v32
	v_mov_b32_e32 v41, v32
	v_mov_b32_e32 v42, v32
	v_mov_b32_e32 v43, v32
	v_mov_b32_e32 v44, v32
	v_mov_b32_e32 v45, v32
	v_mov_b32_e32 v46, v32
	v_mov_b32_e32 v47, v32
	v_mov_b32_e32 v48, v32
	v_mov_b32_e32 v49, v32
	v_mov_b32_e32 v50, v32
	v_mov_b32_e32 v51, v32
	s_waitcnt vmcnt(5)
	v_mov_b32_e32 v52, v32
	v_mov_b32_e32 v53, v32
	v_mov_b32_e32 v54, v32
	v_mov_b32_e32 v55, v32
	v_mov_b32_e32 v56, v32
	v_mov_b32_e32 v57, v32
	v_mov_b32_e32 v58, v32
	v_mov_b32_e32 v59, v32
	v_mov_b32_e32 v60, v32
	v_mov_b32_e32 v61, v32
	v_mov_b32_e32 v62, v32
	v_mov_b32_e32 v63, v32
	v_mov_b32_e32 v64, v32
	v_mov_b32_e32 v65, v32
	v_mov_b32_e32 v66, v32
	v_mov_b32_e32 v67, v32
	v_mov_b32_e32 v68, v32
	v_mov_b32_e32 v69, v32
	v_mov_b32_e32 v70, v32
	v_mov_b32_e32 v71, v32
	v_mov_b32_e32 v72, v32
	v_mov_b32_e32 v73, v32
	v_mov_b32_e32 v74, v32
	v_mov_b32_e32 v75, v32
	v_mov_b32_e32 v76, v32
	v_mov_b32_e32 v77, v32
	v_mov_b32_e32 v78, v32
	v_mov_b32_e32 v79, v32
	v_mov_b32_e32 v80, v32
	v_mov_b32_e32 v81, v32
	v_mov_b32_e32 v82, v32
	v_mov_b32_e32 v83, v32
	v_mov_b32_e32 v84, v32
	v_mov_b32_e32 v85, v32
	v_mov_b32_e32 v86, v32
	v_mov_b32_e32 v87, v32
	v_mov_b32_e32 v88, v32
	v_mov_b32_e32 v89, v32
	v_mov_b32_e32 v90, v32
	v_mov_b32_e32 v91, v32
	v_mov_b32_e32 v92, v32
	v_mov_b32_e32 v93, v32
	v_mov_b32_e32 v94, v32
	v_mov_b32_e32 v95, v32
	s_waitcnt vmcnt(0)
